# SO6: lora up-projection weights copied to LDS once per chain (16 KiB static LDS) and read from there by the hand-written side work, instead of 16 global loads per wave and block
# speedup vs baseline: 1.0146x; 1.0098x over previous
.LBB0_382:
	s_andn2_b64 vcc, exec, s[10:11]
	s_cbranch_vccnz .LBB0_454
	s_and_b64 s[10:11], s[12:13], exec
	s_cselect_b32 s10, 4, 2
	s_lshr_b32 s5, s0, 7
	s_lshl_b32 s7, s5, 12
	s_lshl_b32 s3, s1, 3
	s_add_i32 s33, s74, -1
	s_add_i32 s75, s7, 0
	s_bfe_u32 s11, s0, 0x10006
	s_bitcmp1_b32 s0, 6
	s_cselect_b64 s[88:89], -1, 0
	s_and_b32 s0, s0, 0x3fffff80
	s_lshl_b32 s0, s0, 2
	s_add_i32 s62, s0, 0
	s_lshl_b32 s0, s1, 12
	s_add_i32 s7, s0, 0
	s_lshl_b32 s0, s1, 10
	s_lshl_b32 s77, s5, 10
	s_add_i32 s0, s0, 0
	s_lshl_b32 s5, s1, 11
	s_add_i32 s44, s0, 0x1e800
	s_add_i32 s51, s0, 0x1a800
	s_add_i32 s5, s5, 0
	s_add_i32 s18, s0, 0x1b800
	s_add_i32 s12, s1, -4
	s_lshl_b32 s0, s30, 16
	s_lshl_b32 s13, s56, 12
	s_add_i32 s76, s75, 0x14800
	s_add_i32 s62, s62, 0x1f800
	s_add_i32 s63, s74, 0xffffff80
	s_lshl_b32 s59, s56, 6
	s_add_i32 s5, s5, 0x1c800
	s_or_b32 s14, s13, s0
	s_lshl_b32 s13, s12, 1
	s_add_i32 s71, s74, -8
	s_lshl_b32 s0, s12, 4
	s_cmp_lt_u32 s1, s10
	s_cselect_b64 s[90:91], -1, 0
	s_lshl_b32 s12, s12, 11
	v_readlane_b32 s16, v255, 29
	s_add_i32 s34, s12, 0
	s_or_b32 s12, s13, 1
	v_readlane_b32 s17, v255, 30
	s_lshl_b32 s60, s12, 3
	s_lshl_b32 s12, s12, 10
	s_lshl_b32 s10, s11, 10
	s_lshl_b32 s35, s1, 5
	s_lshl_b32 s15, s30, 11
	s_lshl_b32 s11, s11, 5
	s_nor_b64 s[92:93], s[82:83], s[16:17]
	s_add_i32 s61, s12, 0
	s_lshl_b32 s12, s56, 3
	v_readlane_b32 s13, v255, 23
	s_add_u32 s12, s13, s12
	v_readlane_b32 s13, v255, 24
	s_addc_u32 s13, s13, 0
	s_lshl_b32 s16, s30, 2
	s_add_u32 s94, s12, s16
	s_addc_u32 s95, s13, 0
	s_lshl_b32 s12, s30, 7
	s_add_u32 s96, s54, s12
	s_addc_u32 s97, s55, 0
	s_lshl_b32 s12, s56, 7
	s_add_u32 s54, s36, s12
	s_addc_u32 s55, s37, 0
	s_add_u32 s52, s52, s12
	s_addc_u32 s53, s53, 0
	s_add_u32 s12, s42, s12
	s_addc_u32 s13, s43, 0
	s_add_i32 s15, s81, s15
	s_add_i32 s15, s15, s31
	v_writelane_b32 v255, s56, 59
	s_mov_b32 s42, s18
	s_add_i32 s66, s48, s33
	s_add_i32 s67, s15, 0x800
	s_or_b32 s70, s10, 0x18800
	s_lshl_b32 s30, s14, 1
	s_lshl_b32 s72, s11, 1
	v_lshrrev_b32_e32 v34, 3, v1
	v_and_b32_e32 v35, 7, v1
	v_lshlrev_b32_e32 v35, 4, v35
	v_add_u32_e32 v34, s3, v34
	v_mov_b32_e32 v36, s12
	v_mov_b32_e32 v37, s13
	v_mov_b32_e32 v38, s52
	v_mov_b32_e32 v39, s53
	v_mov_b32_e32 v40, s54
	v_mov_b32_e32 v41, s55
	v_mov_b32_e32 v42, s96
	v_mov_b32_e32 v43, s97
	v_lshl_add_u64 v[44:45], v[42:43], 0, s[68:69]
	v_mov_b32_e32 v49, 0x800
	v_mov_b32_e32 v50, 0x200
	v_mov_b32_e32 v46, v34
	v_min_i32_e32 v46, 0x149, v46
	v_mul_hi_i32 v47, v46, s6
	v_ashrrev_i32_e32 v47, 1, v47
	v_mul_u32_u24_e32 v48, 5, v47
	v_sub_u32_e32 v48, v46, v48
	v_mov_b32_e32 v226, v47
	v_cmp_gt_u32_e32 vcc, 3, v48
	v_mov_b32_e32 v51, v36
	v_mov_b32_e32 v52, v37
	v_cndmask_b32_e32 v227, v50, v49, vcc
	v_cmp_eq_u32_e32 vcc, 1, v48
	s_nop 1
	v_cndmask_b32_e32 v51, v51, v38, vcc
	v_cndmask_b32_e32 v52, v52, v39, vcc
	v_cmp_eq_u32_e32 vcc, 2, v48
	s_nop 1
	v_cndmask_b32_e32 v51, v51, v40, vcc
	v_cndmask_b32_e32 v52, v52, v41, vcc
	v_cmp_eq_u32_e32 vcc, 3, v48
	s_nop 1
	v_cndmask_b32_e32 v51, v51, v42, vcc
	v_cndmask_b32_e32 v52, v52, v43, vcc
	v_cmp_eq_u32_e32 vcc, 4, v48
	s_nop 1
	v_cndmask_b32_e32 v51, v51, v44, vcc
	v_cndmask_b32_e32 v52, v52, v45, vcc
	v_mul_lo_u32 v53, s48, v227
	v_add_u32_e32 v53, v53, v35
	v_add_co_u32_e32 v228, vcc, v51, v53
	s_nop 1
	v_addc_co_u32_e32 v229, vcc, 0, v52, vcc
	v_add_u32_e32 v46, 64, v34
	v_min_i32_e32 v46, 0x149, v46
	v_mul_hi_i32 v47, v46, s6
	v_ashrrev_i32_e32 v47, 1, v47
	v_mul_u32_u24_e32 v48, 5, v47
	v_sub_u32_e32 v48, v46, v48
	v_mov_b32_e32 v230, v47
	v_cmp_gt_u32_e32 vcc, 3, v48
	v_mov_b32_e32 v51, v36
	v_mov_b32_e32 v52, v37
	v_cndmask_b32_e32 v231, v50, v49, vcc
	v_cmp_eq_u32_e32 vcc, 1, v48
	s_nop 1
	v_cndmask_b32_e32 v51, v51, v38, vcc
	v_cndmask_b32_e32 v52, v52, v39, vcc
	v_cmp_eq_u32_e32 vcc, 2, v48
	s_nop 1
	v_cndmask_b32_e32 v51, v51, v40, vcc
	v_cndmask_b32_e32 v52, v52, v41, vcc
	v_cmp_eq_u32_e32 vcc, 3, v48
	s_nop 1
	v_cndmask_b32_e32 v51, v51, v42, vcc
	v_cndmask_b32_e32 v52, v52, v43, vcc
	v_cmp_eq_u32_e32 vcc, 4, v48
	s_nop 1
	v_cndmask_b32_e32 v51, v51, v44, vcc
	v_cndmask_b32_e32 v52, v52, v45, vcc
	v_mul_lo_u32 v53, s48, v231
	v_add_u32_e32 v53, v53, v35
	v_add_co_u32_e32 v232, vcc, v51, v53
	s_nop 1
	v_addc_co_u32_e32 v233, vcc, 0, v52, vcc
	v_add_u32_e32 v46, 128, v34
	v_min_i32_e32 v46, 0x149, v46
	v_mul_hi_i32 v47, v46, s6
	v_ashrrev_i32_e32 v47, 1, v47
	v_mul_u32_u24_e32 v48, 5, v47
	v_sub_u32_e32 v48, v46, v48
	v_mov_b32_e32 v234, v47
	v_cmp_gt_u32_e32 vcc, 3, v48
	v_mov_b32_e32 v51, v36
	v_mov_b32_e32 v52, v37
	v_cndmask_b32_e32 v235, v50, v49, vcc
	v_cmp_eq_u32_e32 vcc, 1, v48
	s_nop 1
	v_cndmask_b32_e32 v51, v51, v38, vcc
	v_cndmask_b32_e32 v52, v52, v39, vcc
	v_cmp_eq_u32_e32 vcc, 2, v48
	s_nop 1
	v_cndmask_b32_e32 v51, v51, v40, vcc
	v_cndmask_b32_e32 v52, v52, v41, vcc
	v_cmp_eq_u32_e32 vcc, 3, v48
	s_nop 1
	v_cndmask_b32_e32 v51, v51, v42, vcc
	v_cndmask_b32_e32 v52, v52, v43, vcc
	v_cmp_eq_u32_e32 vcc, 4, v48
	s_nop 1
	v_cndmask_b32_e32 v51, v51, v44, vcc
	v_cndmask_b32_e32 v52, v52, v45, vcc
	v_mul_lo_u32 v53, s48, v235
	v_add_u32_e32 v53, v53, v35
	v_add_co_u32_e32 v236, vcc, v51, v53
	s_nop 1
	v_addc_co_u32_e32 v237, vcc, 0, v52, vcc
	v_add_u32_e32 v46, 192, v34
	v_min_i32_e32 v46, 0x149, v46
	v_mul_hi_i32 v47, v46, s6
	v_ashrrev_i32_e32 v47, 1, v47
	v_mul_u32_u24_e32 v48, 5, v47
	v_sub_u32_e32 v48, v46, v48
	v_mov_b32_e32 v238, v47
	v_cmp_gt_u32_e32 vcc, 3, v48
	v_mov_b32_e32 v51, v36
	v_mov_b32_e32 v52, v37
	v_cndmask_b32_e32 v239, v50, v49, vcc
	v_cmp_eq_u32_e32 vcc, 1, v48
	s_nop 1
	v_cndmask_b32_e32 v51, v51, v38, vcc
	v_cndmask_b32_e32 v52, v52, v39, vcc
	v_cmp_eq_u32_e32 vcc, 2, v48
	s_nop 1
	v_cndmask_b32_e32 v51, v51, v40, vcc
	v_cndmask_b32_e32 v52, v52, v41, vcc
	v_cmp_eq_u32_e32 vcc, 3, v48
	s_nop 1
	v_cndmask_b32_e32 v51, v51, v42, vcc
	v_cndmask_b32_e32 v52, v52, v43, vcc
	v_cmp_eq_u32_e32 vcc, 4, v48
	s_nop 1
	v_cndmask_b32_e32 v51, v51, v44, vcc
	v_cndmask_b32_e32 v52, v52, v45, vcc
	v_mul_lo_u32 v53, s48, v239
	v_add_u32_e32 v53, v53, v35
	v_add_co_u32_e32 v240, vcc, v51, v53
	s_nop 1
	v_addc_co_u32_e32 v241, vcc, 0, v52, vcc
	v_add_u32_e32 v46, 256, v34
	v_min_i32_e32 v46, 0x149, v46
	v_mul_hi_i32 v47, v46, s6
	v_ashrrev_i32_e32 v47, 1, v47
	v_mul_u32_u24_e32 v48, 5, v47
	v_sub_u32_e32 v48, v46, v48
	v_mov_b32_e32 v242, v47
	v_cmp_gt_u32_e32 vcc, 3, v48
	v_mov_b32_e32 v51, v36
	v_mov_b32_e32 v52, v37
	v_cndmask_b32_e32 v243, v50, v49, vcc
	v_cmp_eq_u32_e32 vcc, 1, v48
	s_nop 1
	v_cndmask_b32_e32 v51, v51, v38, vcc
	v_cndmask_b32_e32 v52, v52, v39, vcc
	v_cmp_eq_u32_e32 vcc, 2, v48
	s_nop 1
	v_cndmask_b32_e32 v51, v51, v40, vcc
	v_cndmask_b32_e32 v52, v52, v41, vcc
	v_cmp_eq_u32_e32 vcc, 3, v48
	s_nop 1
	v_cndmask_b32_e32 v51, v51, v42, vcc
	v_cndmask_b32_e32 v52, v52, v43, vcc
	v_cmp_eq_u32_e32 vcc, 4, v48
	s_nop 1
	v_cndmask_b32_e32 v51, v51, v44, vcc
	v_cndmask_b32_e32 v52, v52, v45, vcc
	v_mul_lo_u32 v53, s48, v243
	v_add_u32_e32 v53, v53, v35
	v_add_co_u32_e32 v244, vcc, v51, v53
	s_nop 1
	v_addc_co_u32_e32 v245, vcc, 0, v52, vcc
	v_add_u32_e32 v46, 320, v34
	v_min_i32_e32 v46, 0x149, v46
	v_mul_hi_i32 v47, v46, s6
	v_ashrrev_i32_e32 v47, 1, v47
	v_mul_u32_u24_e32 v48, 5, v47
	v_sub_u32_e32 v48, v46, v48
	v_mov_b32_e32 v246, v47
	v_cmp_gt_u32_e32 vcc, 3, v48
	v_mov_b32_e32 v51, v36
	v_mov_b32_e32 v52, v37
	v_cndmask_b32_e32 v247, v50, v49, vcc
	v_cmp_eq_u32_e32 vcc, 1, v48
	s_nop 1
	v_cndmask_b32_e32 v51, v51, v38, vcc
	v_cndmask_b32_e32 v52, v52, v39, vcc
	v_cmp_eq_u32_e32 vcc, 2, v48
	s_nop 1
	v_cndmask_b32_e32 v51, v51, v40, vcc
	v_cndmask_b32_e32 v52, v52, v41, vcc
	v_cmp_eq_u32_e32 vcc, 3, v48
	s_nop 1
	v_cndmask_b32_e32 v51, v51, v42, vcc
	v_cndmask_b32_e32 v52, v52, v43, vcc
	v_cmp_eq_u32_e32 vcc, 4, v48
	s_nop 1
	v_cndmask_b32_e32 v51, v51, v44, vcc
	v_cndmask_b32_e32 v52, v52, v45, vcc
	v_mul_lo_u32 v53, s48, v247
	v_add_u32_e32 v53, v53, v35
	v_add_co_u32_e32 v248, vcc, v51, v53
	s_nop 1
	v_addc_co_u32_e32 v249, vcc, 0, v52, vcc
	v_readlane_b32 s10, v255, 25
	v_readlane_b32 s11, v255, 26
	v_lshlrev_b32_e32 v34, 7, v1
	v_lshrrev_b32_e32 v36, 1, v1
	v_and_b32_e32 v34, 0x780, v34
	v_and_b32_e32 v36, -8, v36
	v_mov_b32_e32 v35, 0
	v_lshl_add_u32 v34, v36, 1, v34
	s_lshr_b32 s12, s1, 2
	s_lshl_b32 s12, s12, 18
	s_and_b32 s13, s1, 3
	s_lshl_b32 s13, s13, 11
	s_add_i32 s12, s12, s13
	s_add_i32 s12, s12, s30
	s_mov_b32 s13, 0
	v_lshl_add_u64 v[36:37], s[10:11], 0, v[34:35]
	v_lshl_add_u64 v[36:37], v[36:37], 0, s[12:13]
	s_lshl_b32 s12, s1, 11
	s_add_i32 s12, s12, 0x24000
	s_mov_b32 s13, m0
	s_mov_b32 m0, s12
	s_nop 0
	global_load_lds_dwordx4 v[36:37], off
	s_add_i32 s12, s12, 0x3c0
	s_mov_b32 m0, s12
	s_nop 0
	global_load_lds_dwordx4 v[36:37], off offset:64
	s_mov_b32 m0, s13
	s_branch .LBB0_385

.LBB0_436:
	s_waitcnt vmcnt(0)
	s_or_b64 s[10:11], s[82:83], s[56:57]
	s_and_b64 vcc, exec, s[10:11]
	s_waitcnt lgkmcnt(0)
	s_barrier
	s_cbranch_vccnz .LBB0_438
	s_lshl_b32 s15, s49, 6
	s_sub_i32 s16, s63, s73
	s_add_i32 s17, s15, s0
	s_sub_i32 s18, s71, s17
	s_add_i32 s14, s15, s60
	s_sub_i32 s31, s71, s14
	s_and_b64 s[10:11], s[8:9], exec
	s_cselect_b32 s16, s15, s16
	s_cselect_b32 s17, s17, s18
	s_cselect_b32 s14, s14, s31
	v_lshrrev_b32_e32 v136, 3, v1
	v_and_b32_e32 v137, 7, v1
	v_lshlrev_b32_e32 v143, 4, v1
	v_mov_b32_e32 v144, 0
	v_mov_b32_e32 v145, 0
	v_mov_b32_e32 v146, 0
	v_mov_b32_e32 v147, 0
	v_add_u32_e32 v143, 0x22f00, v143
	v_lshlrev_b32_e32 v138, 4, v137
	v_add_u32_e32 v139, s17, v136
	v_add_u32_e32 v140, s14, v136
	ds_write_b128 v143, v[144:147]
	v_subrev_u32_e32 v98, s16, v139
	v_subrev_u32_e32 v99, s16, v140
	v_cmp_lt_i32_e32 vcc, 0, v139
	v_mad_u32_u24 v98, v98, s58, v138
	v_mad_u32_u24 v99, v99, s58, v138
	v_mov_b32_e32 v141, 0x1a580
	v_mov_b32_e32 v142, 0x1a080
	v_cndmask_b32_e32 v100, v141, v98, vcc
	v_cmp_gt_i32_e32 vcc, s33, v139
	v_lshlrev_b32_e32 v148, 5, v137
	v_add_u32_e32 v148, 0x22000, v148
	v_cndmask_b32_e32 v101, v142, v98, vcc
	v_cmp_lt_i32_e32 vcc, 0, v140
	ds_read_b128 v[168:171], v100 offset:35200
	ds_read_b128 v[172:175], v98 offset:35840
	ds_read_b128 v[176:179], v101 offset:36480
	ds_read_b128 v[192:195], v148 offset:768
	ds_read_b128 v[196:199], v148 offset:784
	v_cndmask_b32_e32 v220, v141, v99, vcc
	v_cmp_gt_i32_e32 vcc, s33, v140
	ds_read_b128 v[200:203], v148 offset:1024
	ds_read_b128 v[204:207], v148 offset:1040
	v_sub_u32_e32 v149, 7, v136
	v_cndmask_b32_e32 v221, v142, v99, vcc
	ds_read_b128 v[180:183], v100 offset:35328
	ds_read_b128 v[184:187], v98 offset:35968
	ds_read_b128 v[188:191], v101 offset:36608
	v_cndmask_b32_e64 v149, v149, v136, s[8:9]
	v_lshl_add_u32 v149, v149, 7, v138
	v_add_u32_e32 v222, s34, v149
	v_add_u32_e32 v223, s61, v149
	v_lshlrev_b32_e32 v224, 4, v1
	v_add_u32_e32 v224, 0x24000, v224
	s_waitcnt lgkmcnt(7)
	v_lshlrev_b32_e32 v136, 16, v168
	v_lshlrev_b32_e32 v138, 16, v176
	v_and_b32_e32 v137, 0xffff0000, v168
	v_lshlrev_b32_e32 v140, 16, v172
	v_and_b32_e32 v139, 0xffff0000, v176
	v_lshlrev_b32_e32 v142, 16, v169
	v_add_f32_e32 v136, v138, v136
	v_and_b32_e32 v141, 0xffff0000, v172
	v_lshlrev_b32_e32 v144, 16, v177
	v_and_b32_e32 v143, 0xffff0000, v169
	v_fma_f32 v136, v136, 0.5, -v140
	v_add_f32_e32 v137, v139, v137
	v_lshlrev_b32_e32 v146, 16, v173
	v_and_b32_e32 v145, 0xffff0000, v177
	v_lshlrev_b32_e32 v148, 16, v170
	s_waitcnt lgkmcnt(5)
	v_fmac_f32_e32 v140, v192, v136
	v_fma_f32 v137, v137, 0.5, -v141
	v_add_f32_e32 v142, v144, v142
	v_and_b32_e32 v147, 0xffff0000, v173
	v_lshlrev_b32_e32 v150, 16, v178
	v_and_b32_e32 v149, 0xffff0000, v170
	v_mul_f32_e32 v140, 0x4038aa3b, v140
	v_fmac_f32_e32 v141, v193, v137
	v_fma_f32 v142, v142, 0.5, -v146
	v_add_f32_e32 v143, v145, v143
	v_lshlrev_b32_e32 v152, 16, v174
	v_and_b32_e32 v151, 0xffff0000, v178
	v_lshlrev_b32_e32 v154, 16, v171
	v_exp_f32_e32 v140, v140
	v_mul_f32_e32 v141, 0x4038aa3b, v141
	v_fmac_f32_e32 v146, v194, v142
	v_fma_f32 v143, v143, 0.5, -v147
	v_add_f32_e32 v148, v150, v148
	v_and_b32_e32 v153, 0xffff0000, v174
	v_lshlrev_b32_e32 v156, 16, v179
	v_and_b32_e32 v155, 0xffff0000, v171
	v_add_f32_e32 v140, 1.0, v140
	v_exp_f32_e32 v141, v141
	v_mul_f32_e32 v146, 0x4038aa3b, v146
	v_fmac_f32_e32 v147, v195, v143
	v_fma_f32 v148, v148, 0.5, -v152
	v_add_f32_e32 v149, v151, v149
	v_lshlrev_b32_e32 v158, 16, v175
	v_and_b32_e32 v157, 0xffff0000, v179
	v_rcp_f32_e32 v140, v140
	v_add_f32_e32 v141, 1.0, v141
	v_exp_f32_e32 v146, v146
	v_mul_f32_e32 v147, 0x4038aa3b, v147
	v_fmac_f32_e32 v152, v196, v148
	v_fma_f32 v149, v149, 0.5, -v153
	v_add_f32_e32 v154, v156, v154
	v_and_b32_e32 v159, 0xffff0000, v175
	ds_read_b128 v[168:171], v220 offset:35200
	ds_read_b128 v[172:175], v99 offset:35840
	ds_read_b128 v[176:179], v221 offset:36480
	v_fma_f32 v140, -v140, 2.0, 1.0
	v_rcp_f32_e32 v141, v141
	v_add_f32_e32 v146, 1.0, v146
	v_exp_f32_e32 v147, v147
	v_mul_f32_e32 v152, 0x4038aa3b, v152
	v_fmac_f32_e32 v153, v197, v149
	v_fma_f32 v154, v154, 0.5, -v158
	v_add_f32_e32 v155, v157, v155
	v_fma_f32 v141, -v141, 2.0, 1.0
	v_rcp_f32_e32 v146, v146
	v_add_f32_e32 v147, 1.0, v147
	v_exp_f32_e32 v152, v152
	v_mul_f32_e32 v153, 0x4038aa3b, v153
	v_fmac_f32_e32 v158, v198, v154
	v_fma_f32 v155, v155, 0.5, -v159
	s_waitcnt lgkmcnt(3)
	v_lshlrev_b32_e32 v136, 16, v180
	v_cvt_pk_bf16_f32 v160, v140, v141
	v_fma_f32 v146, -v146, 2.0, 1.0
	v_rcp_f32_e32 v147, v147
	v_add_f32_e32 v152, 1.0, v152
	v_exp_f32_e32 v153, v153
	v_mul_f32_e32 v158, 0x4038aa3b, v158
	v_fmac_f32_e32 v159, v199, v155
	v_lshlrev_b32_e32 v138, 16, v188
	v_and_b32_e32 v137, 0xffff0000, v180
	v_fma_f32 v147, -v147, 2.0, 1.0
	v_rcp_f32_e32 v152, v152
	v_add_f32_e32 v153, 1.0, v153
	v_exp_f32_e32 v158, v158
	v_mul_f32_e32 v159, 0x4038aa3b, v159
	v_lshlrev_b32_e32 v140, 16, v184
	v_and_b32_e32 v139, 0xffff0000, v188
	v_lshlrev_b32_e32 v142, 16, v181
	v_cvt_pk_bf16_f32 v161, v146, v147
	v_fma_f32 v152, -v152, 2.0, 1.0
	v_rcp_f32_e32 v153, v153
	v_add_f32_e32 v158, 1.0, v158
	v_exp_f32_e32 v159, v159
	v_add_f32_e32 v136, v138, v136
	v_and_b32_e32 v141, 0xffff0000, v184
	v_lshlrev_b32_e32 v144, 16, v189
	v_and_b32_e32 v143, 0xffff0000, v181
	v_fma_f32 v153, -v153, 2.0, 1.0
	v_rcp_f32_e32 v158, v158
	v_add_f32_e32 v159, 1.0, v159
	v_fma_f32 v136, v136, 0.5, -v140
	v_add_f32_e32 v137, v139, v137
	v_lshlrev_b32_e32 v146, 16, v185
	v_and_b32_e32 v145, 0xffff0000, v189
	v_lshlrev_b32_e32 v148, 16, v182
	v_cvt_pk_bf16_f32 v162, v152, v153
	v_fma_f32 v158, -v158, 2.0, 1.0
	v_rcp_f32_e32 v159, v159
	v_fmac_f32_e32 v140, v200, v136
	v_fma_f32 v137, v137, 0.5, -v141
	v_add_f32_e32 v142, v144, v142
	v_and_b32_e32 v147, 0xffff0000, v185
	v_lshlrev_b32_e32 v150, 16, v190
	v_and_b32_e32 v149, 0xffff0000, v182
	v_fma_f32 v159, -v159, 2.0, 1.0
	v_fmac_f32_e32 v141, v201, v137
	v_fma_f32 v142, v142, 0.5, -v146
	v_add_f32_e32 v143, v145, v143
	v_lshlrev_b32_e32 v152, 16, v186
	v_and_b32_e32 v151, 0xffff0000, v190
	v_lshlrev_b32_e32 v154, 16, v183
	v_cvt_pk_bf16_f32 v163, v158, v159
	ds_write_b128 v222, v[160:163] offset:16384
	s_waitcnt lgkmcnt(1)
	v_lshlrev_b32_e32 v136, 16, v168
	v_cvt_pk_bf16_f32 v216, v140, v141
	v_fmac_f32_e32 v146, v202, v142
	v_fma_f32 v143, v143, 0.5, -v147
	v_add_f32_e32 v148, v150, v148
	v_and_b32_e32 v153, 0xffff0000, v186
	v_lshlrev_b32_e32 v156, 16, v191
	v_and_b32_e32 v155, 0xffff0000, v183
	v_lshlrev_b32_e32 v138, 16, v176
	v_and_b32_e32 v137, 0xffff0000, v168
	v_fmac_f32_e32 v147, v203, v143
	v_fma_f32 v148, v148, 0.5, -v152
	v_add_f32_e32 v149, v151, v149
	v_lshlrev_b32_e32 v158, 16, v187
	v_and_b32_e32 v157, 0xffff0000, v191
	v_lshlrev_b32_e32 v140, 16, v172
	v_and_b32_e32 v139, 0xffff0000, v176
	v_lshlrev_b32_e32 v142, 16, v169
	v_cvt_pk_bf16_f32 v217, v146, v147
	v_fmac_f32_e32 v152, v204, v148
	v_fma_f32 v149, v149, 0.5, -v153
	v_add_f32_e32 v154, v156, v154
	v_and_b32_e32 v159, 0xffff0000, v187
	ds_read_b128 v[180:183], v220 offset:35328
	ds_read_b128 v[184:187], v99 offset:35968
	ds_read_b128 v[188:191], v221 offset:36608
	v_add_f32_e32 v136, v138, v136
	v_and_b32_e32 v141, 0xffff0000, v172
	v_lshlrev_b32_e32 v144, 16, v177
	v_and_b32_e32 v143, 0xffff0000, v169
	v_fmac_f32_e32 v153, v205, v149
	v_fma_f32 v154, v154, 0.5, -v158
	v_add_f32_e32 v155, v157, v155
	v_fma_f32 v136, v136, 0.5, -v140
	v_add_f32_e32 v137, v139, v137
	v_lshlrev_b32_e32 v146, 16, v173
	v_and_b32_e32 v145, 0xffff0000, v177
	v_lshlrev_b32_e32 v148, 16, v170
	v_cvt_pk_bf16_f32 v218, v152, v153
	v_fmac_f32_e32 v158, v206, v154
	v_fma_f32 v155, v155, 0.5, -v159
	v_fmac_f32_e32 v140, v192, v136
	v_fma_f32 v137, v137, 0.5, -v141
	v_add_f32_e32 v142, v144, v142
	v_and_b32_e32 v147, 0xffff0000, v173
	v_lshlrev_b32_e32 v150, 16, v178
	v_and_b32_e32 v149, 0xffff0000, v170
	v_fmac_f32_e32 v159, v207, v155
	v_mul_f32_e32 v140, 0x4038aa3b, v140
	v_fmac_f32_e32 v141, v193, v137
	v_fma_f32 v142, v142, 0.5, -v146
	v_add_f32_e32 v143, v145, v143
	v_lshlrev_b32_e32 v152, 16, v174
	v_and_b32_e32 v151, 0xffff0000, v178
	v_lshlrev_b32_e32 v154, 16, v171
	v_cvt_pk_bf16_f32 v219, v158, v159
	ds_write_b128 v222, v[216:219] offset:24576
	v_exp_f32_e32 v140, v140
	v_mul_f32_e32 v141, 0x4038aa3b, v141
	v_fmac_f32_e32 v146, v194, v142
	v_fma_f32 v143, v143, 0.5, -v147
	v_add_f32_e32 v148, v150, v148
	v_and_b32_e32 v153, 0xffff0000, v174
	v_lshlrev_b32_e32 v156, 16, v179
	v_and_b32_e32 v155, 0xffff0000, v171
	v_add_f32_e32 v140, 1.0, v140
	v_exp_f32_e32 v141, v141
	v_mul_f32_e32 v146, 0x4038aa3b, v146
	v_fmac_f32_e32 v147, v195, v143
	v_fma_f32 v148, v148, 0.5, -v152
	v_add_f32_e32 v149, v151, v149
	v_lshlrev_b32_e32 v158, 16, v175
	v_and_b32_e32 v157, 0xffff0000, v179
	v_rcp_f32_e32 v140, v140
	v_add_f32_e32 v141, 1.0, v141
	v_exp_f32_e32 v146, v146
	v_mul_f32_e32 v147, 0x4038aa3b, v147
	v_fmac_f32_e32 v152, v196, v148
	v_fma_f32 v149, v149, 0.5, -v153
	v_add_f32_e32 v154, v156, v154
	v_and_b32_e32 v159, 0xffff0000, v175
	v_fma_f32 v140, -v140, 2.0, 1.0
	v_rcp_f32_e32 v141, v141
	v_add_f32_e32 v146, 1.0, v146
	v_exp_f32_e32 v147, v147
	v_mul_f32_e32 v152, 0x4038aa3b, v152
	v_fmac_f32_e32 v153, v197, v149
	v_fma_f32 v154, v154, 0.5, -v158
	v_add_f32_e32 v155, v157, v155
	v_fma_f32 v141, -v141, 2.0, 1.0
	v_rcp_f32_e32 v146, v146
	v_add_f32_e32 v147, 1.0, v147
	v_exp_f32_e32 v152, v152
	v_mul_f32_e32 v153, 0x4038aa3b, v153
	v_fmac_f32_e32 v158, v198, v154
	v_fma_f32 v155, v155, 0.5, -v159
	s_waitcnt lgkmcnt(1)
	v_lshlrev_b32_e32 v136, 16, v180
	v_cvt_pk_bf16_f32 v160, v140, v141
	v_fma_f32 v146, -v146, 2.0, 1.0
	v_rcp_f32_e32 v147, v147
	v_add_f32_e32 v152, 1.0, v152
	v_exp_f32_e32 v153, v153
	v_mul_f32_e32 v158, 0x4038aa3b, v158
	v_fmac_f32_e32 v159, v199, v155
	v_lshlrev_b32_e32 v138, 16, v188
	v_and_b32_e32 v137, 0xffff0000, v180
	v_fma_f32 v147, -v147, 2.0, 1.0
	v_rcp_f32_e32 v152, v152
	v_add_f32_e32 v153, 1.0, v153
	v_exp_f32_e32 v158, v158
	v_mul_f32_e32 v159, 0x4038aa3b, v159
	v_lshlrev_b32_e32 v140, 16, v184
	v_and_b32_e32 v139, 0xffff0000, v188
	v_lshlrev_b32_e32 v142, 16, v181
	v_cvt_pk_bf16_f32 v161, v146, v147
	v_fma_f32 v152, -v152, 2.0, 1.0
	v_rcp_f32_e32 v153, v153
	v_add_f32_e32 v158, 1.0, v158
	v_exp_f32_e32 v159, v159
	v_add_f32_e32 v136, v138, v136
	v_and_b32_e32 v141, 0xffff0000, v184
	v_lshlrev_b32_e32 v144, 16, v189
	v_and_b32_e32 v143, 0xffff0000, v181
	v_fma_f32 v153, -v153, 2.0, 1.0
	v_rcp_f32_e32 v158, v158
	v_add_f32_e32 v159, 1.0, v159
	v_fma_f32 v136, v136, 0.5, -v140
	v_add_f32_e32 v137, v139, v137
	v_lshlrev_b32_e32 v146, 16, v185
	v_and_b32_e32 v145, 0xffff0000, v189
	v_lshlrev_b32_e32 v148, 16, v182
	v_cvt_pk_bf16_f32 v162, v152, v153
	v_fma_f32 v158, -v158, 2.0, 1.0
	v_rcp_f32_e32 v159, v159
	v_fmac_f32_e32 v140, v200, v136
	v_fma_f32 v137, v137, 0.5, -v141
	v_add_f32_e32 v142, v144, v142
	v_and_b32_e32 v147, 0xffff0000, v185
	v_lshlrev_b32_e32 v150, 16, v190
	v_and_b32_e32 v149, 0xffff0000, v182
	v_fma_f32 v159, -v159, 2.0, 1.0
	v_fmac_f32_e32 v141, v201, v137
	v_fma_f32 v142, v142, 0.5, -v146
	v_add_f32_e32 v143, v145, v143
	v_lshlrev_b32_e32 v152, 16, v186
	v_and_b32_e32 v151, 0xffff0000, v190
	v_lshlrev_b32_e32 v154, 16, v183
	v_cvt_pk_bf16_f32 v163, v158, v159
	ds_write_b128 v223, v[160:163] offset:16384
	v_cvt_pk_bf16_f32 v216, v140, v141
	v_fmac_f32_e32 v146, v202, v142
	v_fma_f32 v143, v143, 0.5, -v147
	v_add_f32_e32 v148, v150, v148
	v_and_b32_e32 v153, 0xffff0000, v186
	v_lshlrev_b32_e32 v156, 16, v191
	v_and_b32_e32 v155, 0xffff0000, v183
	v_fmac_f32_e32 v147, v203, v143
	v_fma_f32 v148, v148, 0.5, -v152
	v_add_f32_e32 v149, v151, v149
	v_lshlrev_b32_e32 v158, 16, v187
	v_and_b32_e32 v157, 0xffff0000, v191
	v_cvt_pk_bf16_f32 v217, v146, v147
	v_fmac_f32_e32 v152, v204, v148
	v_fma_f32 v149, v149, 0.5, -v153
	v_add_f32_e32 v154, v156, v154
	v_and_b32_e32 v159, 0xffff0000, v187
	v_fmac_f32_e32 v153, v205, v149
	v_fma_f32 v154, v154, 0.5, -v158
	v_add_f32_e32 v155, v157, v155
	v_cvt_pk_bf16_f32 v218, v152, v153
	v_fmac_f32_e32 v158, v206, v154
	v_fma_f32 v155, v155, 0.5, -v159
	v_fmac_f32_e32 v159, v207, v155
	v_cvt_pk_bf16_f32 v219, v158, v159
	ds_write_b128 v223, v[216:219] offset:24576
	v_and_b32_e32 v160, 15, v1
	v_and_b32_e32 v161, -16, v1
	v_or_b32_e32 v162, s0, v160
	v_lshrrev_b32_e32 v163, 2, v1
	v_lshl_add_u32 v161, v162, 7, v161
	ds_read_b128 v[136:139], v161 offset:16384
	ds_read_b128 v[140:143], v161 offset:16448
	ds_read_b128 v[34:37], v224 offset:0
	ds_read_b128 v[38:41], v224 offset:1024
	ds_read_b128 v[42:45], v224 offset:2048
	ds_read_b128 v[46:49], v224 offset:3072
	ds_read_b128 v[50:53], v224 offset:4096
	ds_read_b128 v[54:57], v224 offset:5120
	ds_read_b128 v[58:61], v224 offset:6144
	ds_read_b128 v[62:65], v224 offset:7168
	v_lshlrev_b32_e32 v162, 2, v160
	v_and_b32_e32 v163, 0x1fffffc, v163
	v_add_u32_e32 v162, 0x22400, v162
	v_add_lshl_u32 v163, v163, s0, 7
	ds_read2_b32 v[152:153], v162 offset0:64 offset1:80
	ds_read2_b32 v[154:155], v162 offset0:96 offset1:112
	ds_read2_b32 v[156:157], v162 offset0:128 offset1:144
	ds_read2_b32 v[158:159], v162 offset0:160 offset1:176
	v_lshl_add_u32 v163, v160, 1, v163
	s_waitcnt lgkmcnt(10)
	v_mfma_f32_16x16x32_bf16 v[168:171], v[136:139], v[34:37], 0
	v_mfma_f32_16x16x32_bf16 v[168:171], v[140:143], v[38:41], v[168:171]
	s_waitcnt lgkmcnt(8)
	v_mfma_f32_16x16x32_bf16 v[172:175], v[136:139], v[42:45], 0
	v_mfma_f32_16x16x32_bf16 v[172:175], v[140:143], v[46:49], v[172:175]
	s_waitcnt lgkmcnt(0)
	ds_read_b128 v[144:147], v161 offset:24576
	ds_read_b128 v[148:151], v161 offset:24640
	ds_read_b128 v[66:69], v224 offset:8192
	ds_read_b128 v[70:73], v224 offset:9216
	ds_read_b128 v[74:77], v224 offset:10240
	ds_read_b128 v[78:81], v224 offset:11264
	ds_read_b128 v[82:85], v224 offset:12288
	ds_read_b128 v[86:89], v224 offset:13312
	ds_read_b128 v[90:93], v224 offset:14336
	ds_read_b128 v[94:97], v224 offset:15360
	s_nop 7
	v_add_f32_e32 v168, v168, v152
	v_mul_f32_e32 v168, 0xbfb8aa3b, v168
	v_add_f32_e32 v169, v169, v152
	v_exp_f32_e32 v168, v168
	v_mul_f32_e32 v169, 0xbfb8aa3b, v169
	v_add_f32_e32 v170, v170, v152
	v_add_f32_e32 v168, 1.0, v168
	v_exp_f32_e32 v169, v169
	v_mul_f32_e32 v170, 0xbfb8aa3b, v170
	v_add_f32_e32 v171, v171, v152
	v_rcp_f32_e32 v168, v168
	v_add_f32_e32 v169, 1.0, v169
	v_exp_f32_e32 v170, v170
	v_mul_f32_e32 v171, 0xbfb8aa3b, v171
	v_fma_mixlo_f16 v168, v168, s47, 0
	v_rcp_f32_e32 v169, v169
	v_add_f32_e32 v170, 1.0, v170
	v_exp_f32_e32 v171, v171
	ds_write_b16 v163, v168 offset:16384
	v_fma_mixlo_f16 v169, v169, s47, 0
	v_rcp_f32_e32 v170, v170
	v_add_f32_e32 v171, 1.0, v171
	ds_write_b16 v163, v169 offset:16512
	v_fma_mixlo_f16 v170, v170, s47, 0
	v_rcp_f32_e32 v171, v171
	ds_write_b16 v163, v170 offset:16640
	v_fma_mixlo_f16 v171, v171, s47, 0
	ds_write_b16 v163, v171 offset:16768
	v_mfma_f32_16x16x32_bf16 v[176:179], v[136:139], v[50:53], 0
	v_mfma_f32_16x16x32_bf16 v[176:179], v[140:143], v[54:57], v[176:179]
	v_add_f32_e32 v172, v172, v153
	v_mul_f32_e32 v172, 0xbfb8aa3b, v172
	v_add_f32_e32 v173, v173, v153
	v_exp_f32_e32 v172, v172
	v_mul_f32_e32 v173, 0xbfb8aa3b, v173
	v_add_f32_e32 v174, v174, v153
	v_add_f32_e32 v172, 1.0, v172
	v_exp_f32_e32 v173, v173
	v_mul_f32_e32 v174, 0xbfb8aa3b, v174
	v_add_f32_e32 v175, v175, v153
	v_rcp_f32_e32 v172, v172
	v_add_f32_e32 v173, 1.0, v173
	v_exp_f32_e32 v174, v174
	v_mul_f32_e32 v175, 0xbfb8aa3b, v175
	v_fma_mixlo_f16 v172, v172, s47, 0
	v_rcp_f32_e32 v173, v173
	v_add_f32_e32 v174, 1.0, v174
	v_exp_f32_e32 v175, v175
	ds_write_b16 v163, v172 offset:16416
	v_fma_mixlo_f16 v173, v173, s47, 0
	v_rcp_f32_e32 v174, v174
	v_add_f32_e32 v175, 1.0, v175
	ds_write_b16 v163, v173 offset:16544
	v_fma_mixlo_f16 v174, v174, s47, 0
	v_rcp_f32_e32 v175, v175
	ds_write_b16 v163, v174 offset:16672
	v_fma_mixlo_f16 v175, v175, s47, 0
	ds_write_b16 v163, v175 offset:16800
	v_mfma_f32_16x16x32_bf16 v[180:183], v[136:139], v[58:61], 0
	v_mfma_f32_16x16x32_bf16 v[180:183], v[140:143], v[62:65], v[180:183]
	v_add_f32_e32 v176, v176, v154
	v_mul_f32_e32 v176, 0xbfb8aa3b, v176
	v_add_f32_e32 v177, v177, v154
	v_exp_f32_e32 v176, v176
	v_mul_f32_e32 v177, 0xbfb8aa3b, v177
	v_add_f32_e32 v178, v178, v154
	v_add_f32_e32 v176, 1.0, v176
	v_exp_f32_e32 v177, v177
	v_mul_f32_e32 v178, 0xbfb8aa3b, v178
	v_add_f32_e32 v179, v179, v154
	v_rcp_f32_e32 v176, v176
	v_add_f32_e32 v177, 1.0, v177
	v_exp_f32_e32 v178, v178
	v_mul_f32_e32 v179, 0xbfb8aa3b, v179
	v_fma_mixlo_f16 v176, v176, s47, 0
	v_rcp_f32_e32 v177, v177
	v_add_f32_e32 v178, 1.0, v178
	v_exp_f32_e32 v179, v179
	ds_write_b16 v163, v176 offset:16448
	v_fma_mixlo_f16 v177, v177, s47, 0
	v_rcp_f32_e32 v178, v178
	v_add_f32_e32 v179, 1.0, v179
	ds_write_b16 v163, v177 offset:16576
	v_fma_mixlo_f16 v178, v178, s47, 0
	v_rcp_f32_e32 v179, v179
	ds_write_b16 v163, v178 offset:16704
	v_fma_mixlo_f16 v179, v179, s47, 0
	ds_write_b16 v163, v179 offset:16832
	s_waitcnt lgkmcnt(6)
	v_mfma_f32_16x16x32_bf16 v[184:187], v[144:147], v[66:69], 0
	v_mfma_f32_16x16x32_bf16 v[184:187], v[148:151], v[70:73], v[184:187]
	v_add_f32_e32 v180, v180, v155
	v_mul_f32_e32 v180, 0xbfb8aa3b, v180
	v_add_f32_e32 v181, v181, v155
	v_exp_f32_e32 v180, v180
	v_mul_f32_e32 v181, 0xbfb8aa3b, v181
	v_add_f32_e32 v182, v182, v155
	v_add_f32_e32 v180, 1.0, v180
	v_exp_f32_e32 v181, v181
	v_mul_f32_e32 v182, 0xbfb8aa3b, v182
	v_add_f32_e32 v183, v183, v155
	v_rcp_f32_e32 v180, v180
	v_add_f32_e32 v181, 1.0, v181
	v_exp_f32_e32 v182, v182
	v_mul_f32_e32 v183, 0xbfb8aa3b, v183
	v_fma_mixlo_f16 v180, v180, s47, 0
	v_rcp_f32_e32 v181, v181
	v_add_f32_e32 v182, 1.0, v182
	v_exp_f32_e32 v183, v183
	ds_write_b16 v163, v180 offset:16480
	v_fma_mixlo_f16 v181, v181, s47, 0
	v_rcp_f32_e32 v182, v182
	v_add_f32_e32 v183, 1.0, v183
	ds_write_b16 v163, v181 offset:16608
	v_fma_mixlo_f16 v182, v182, s47, 0
	v_rcp_f32_e32 v183, v183
	ds_write_b16 v163, v182 offset:16736
	v_fma_mixlo_f16 v183, v183, s47, 0
	ds_write_b16 v163, v183 offset:16864
	s_waitcnt lgkmcnt(4)
	v_mfma_f32_16x16x32_bf16 v[188:191], v[144:147], v[74:77], 0
	v_mfma_f32_16x16x32_bf16 v[188:191], v[148:151], v[78:81], v[188:191]
	v_add_f32_e32 v184, v184, v156
	v_mul_f32_e32 v184, 0xbfb8aa3b, v184
	v_add_f32_e32 v185, v185, v156
	v_exp_f32_e32 v184, v184
	v_mul_f32_e32 v185, 0xbfb8aa3b, v185
	v_add_f32_e32 v186, v186, v156
	v_add_f32_e32 v184, 1.0, v184
	v_exp_f32_e32 v185, v185
	v_mul_f32_e32 v186, 0xbfb8aa3b, v186
	v_add_f32_e32 v187, v187, v156
	v_rcp_f32_e32 v184, v184
	v_add_f32_e32 v185, 1.0, v185
	v_exp_f32_e32 v186, v186
	v_mul_f32_e32 v187, 0xbfb8aa3b, v187
	v_rcp_f32_e32 v185, v185
	v_add_f32_e32 v186, 1.0, v186
	v_exp_f32_e32 v187, v187
	v_cvt_pk_f16_f32 v184, v184, v185
	v_rcp_f32_e32 v186, v186
	v_add_f32_e32 v187, 1.0, v187
	ds_write_b16 v163, v184 offset:24576
	v_rcp_f32_e32 v187, v187
	ds_write_b16_d16_hi v163, v184 offset:24704
	v_cvt_pk_f16_f32 v186, v186, v187
	ds_write_b16 v163, v186 offset:24832
	ds_write_b16_d16_hi v163, v186 offset:24960
	s_waitcnt lgkmcnt(2)
	v_mfma_f32_16x16x32_bf16 v[192:195], v[144:147], v[82:85], 0
	v_mfma_f32_16x16x32_bf16 v[192:195], v[148:151], v[86:89], v[192:195]
	v_add_f32_e32 v188, v188, v157
	v_mul_f32_e32 v188, 0xbfb8aa3b, v188
	v_add_f32_e32 v189, v189, v157
	v_exp_f32_e32 v188, v188
	v_mul_f32_e32 v189, 0xbfb8aa3b, v189
	v_add_f32_e32 v190, v190, v157
	v_add_f32_e32 v188, 1.0, v188
	v_exp_f32_e32 v189, v189
	v_mul_f32_e32 v190, 0xbfb8aa3b, v190
	v_add_f32_e32 v191, v191, v157
	v_rcp_f32_e32 v188, v188
	v_add_f32_e32 v189, 1.0, v189
	v_exp_f32_e32 v190, v190
	v_mul_f32_e32 v191, 0xbfb8aa3b, v191
	v_rcp_f32_e32 v189, v189
	v_add_f32_e32 v190, 1.0, v190
	v_exp_f32_e32 v191, v191
	v_cvt_pk_f16_f32 v188, v188, v189
	v_rcp_f32_e32 v190, v190
	v_add_f32_e32 v191, 1.0, v191
	ds_write_b16 v163, v188 offset:24608
	v_rcp_f32_e32 v191, v191
	ds_write_b16_d16_hi v163, v188 offset:24736
	v_cvt_pk_f16_f32 v190, v190, v191
	ds_write_b16 v163, v190 offset:24864
	ds_write_b16_d16_hi v163, v190 offset:24992
	s_waitcnt lgkmcnt(0)
	v_mfma_f32_16x16x32_bf16 v[196:199], v[144:147], v[90:93], 0
	v_mfma_f32_16x16x32_bf16 v[196:199], v[148:151], v[94:97], v[196:199]
	v_add_f32_e32 v192, v192, v158
	v_mul_f32_e32 v192, 0xbfb8aa3b, v192
	v_add_f32_e32 v193, v193, v158
	v_exp_f32_e32 v192, v192
	v_mul_f32_e32 v193, 0xbfb8aa3b, v193
	v_add_f32_e32 v194, v194, v158
	v_add_f32_e32 v192, 1.0, v192
	v_exp_f32_e32 v193, v193
	v_mul_f32_e32 v194, 0xbfb8aa3b, v194
	v_add_f32_e32 v195, v195, v158
	v_rcp_f32_e32 v192, v192
	v_add_f32_e32 v193, 1.0, v193
	v_exp_f32_e32 v194, v194
	v_mul_f32_e32 v195, 0xbfb8aa3b, v195
	v_rcp_f32_e32 v193, v193
	v_add_f32_e32 v194, 1.0, v194
	v_exp_f32_e32 v195, v195
	v_cvt_pk_f16_f32 v192, v192, v193
	v_rcp_f32_e32 v194, v194
	v_add_f32_e32 v195, 1.0, v195
	ds_write_b16 v163, v192 offset:24640
	v_rcp_f32_e32 v195, v195
	ds_write_b16_d16_hi v163, v192 offset:24768
	v_cvt_pk_f16_f32 v194, v194, v195
	ds_write_b16 v163, v194 offset:24896
	ds_write_b16_d16_hi v163, v194 offset:25024
	v_add_f32_e32 v196, v196, v159
	v_mul_f32_e32 v196, 0xbfb8aa3b, v196
	v_add_f32_e32 v197, v197, v159
	v_exp_f32_e32 v196, v196
	v_mul_f32_e32 v197, 0xbfb8aa3b, v197
	v_add_f32_e32 v198, v198, v159
	v_add_f32_e32 v196, 1.0, v196
	v_exp_f32_e32 v197, v197
	v_mul_f32_e32 v198, 0xbfb8aa3b, v198
	v_add_f32_e32 v199, v199, v159
	v_rcp_f32_e32 v196, v196
	v_add_f32_e32 v197, 1.0, v197
	v_exp_f32_e32 v198, v198
	v_mul_f32_e32 v199, 0xbfb8aa3b, v199
	v_rcp_f32_e32 v197, v197
	v_add_f32_e32 v198, 1.0, v198
	v_exp_f32_e32 v199, v199
	v_cvt_pk_f16_f32 v196, v196, v197
	v_rcp_f32_e32 v198, v198
	v_add_f32_e32 v199, 1.0, v199
	ds_write_b16 v163, v196 offset:24672
	v_rcp_f32_e32 v199, v199
	ds_write_b16_d16_hi v163, v196 offset:24800
	v_cvt_pk_f16_f32 v198, v198, v199
	ds_write_b16 v163, v198 offset:24928
	ds_write_b16_d16_hi v163, v198 offset:25056

	.amdhsa_kernel _Z10hybrid_fwd6Params
		.amdhsa_group_segment_fixed_size 16384
		.amdhsa_private_segment_fixed_size 0
		.amdhsa_kernarg_size 528
		.amdhsa_user_sgpr_count 2
		.amdhsa_user_sgpr_dispatch_ptr 0
		.amdhsa_user_sgpr_queue_ptr 0
		.amdhsa_user_sgpr_kernarg_segment_ptr 1
		.amdhsa_user_sgpr_dispatch_id 0
		.amdhsa_user_sgpr_kernarg_preload_length 0
		.amdhsa_user_sgpr_kernarg_preload_offset 0
		.amdhsa_user_sgpr_private_segment_size 0
		.amdhsa_uses_dynamic_stack 0
		.amdhsa_enable_private_segment 0
		.amdhsa_system_sgpr_workgroup_id_x 1
		.amdhsa_system_sgpr_workgroup_id_y 0
		.amdhsa_system_sgpr_workgroup_id_z 0
		.amdhsa_system_sgpr_workgroup_info 0
		.amdhsa_system_vgpr_workitem_id 0
		.amdhsa_next_free_vgpr 256
		.amdhsa_next_free_sgpr 98
		.amdhsa_accum_offset 256
		.amdhsa_reserve_vcc 1
		.amdhsa_float_round_mode_32 0
		.amdhsa_float_round_mode_16_64 0
		.amdhsa_float_denorm_mode_32 3
		.amdhsa_float_denorm_mode_16_64 3
		.amdhsa_dx10_clamp 1
		.amdhsa_ieee_mode 1
		.amdhsa_fp16_overflow 0
		.amdhsa_tg_split 0
		.amdhsa_exception_fp_ieee_invalid_op 0
		.amdhsa_exception_fp_denorm_src 0
		.amdhsa_exception_fp_ieee_div_zero 0
		.amdhsa_exception_fp_ieee_overflow 0
		.amdhsa_exception_fp_ieee_underflow 0
		.amdhsa_exception_fp_ieee_inexact 0
		.amdhsa_exception_int_div_zero 0
	.end_amdhsa_kernel

amdhsa.kernels:
  - .agpr_count:     0
    .args:
      - .offset:         0
        .size:           272
        .value_kind:     by_value
      - .offset:         272
        .size:           4
        .value_kind:     hidden_block_count_x
      - .offset:         276
        .size:           4
        .value_kind:     hidden_block_count_y
      - .offset:         280
        .size:           4
        .value_kind:     hidden_block_count_z
      - .offset:         284
        .size:           2
        .value_kind:     hidden_group_size_x
      - .offset:         286
        .size:           2
        .value_kind:     hidden_group_size_y
      - .offset:         288
        .size:           2
        .value_kind:     hidden_group_size_z
      - .offset:         290
        .size:           2
        .value_kind:     hidden_remainder_x
      - .offset:         292
        .size:           2
        .value_kind:     hidden_remainder_y
      - .offset:         294
        .size:           2
        .value_kind:     hidden_remainder_z
      - .offset:         312
        .size:           8
        .value_kind:     hidden_global_offset_x
      - .offset:         320
        .size:           8
        .value_kind:     hidden_global_offset_y
      - .offset:         328
        .size:           8
        .value_kind:     hidden_global_offset_z
      - .offset:         336
        .size:           2
        .value_kind:     hidden_grid_dims
      - .offset:         392
        .size:           4
        .value_kind:     hidden_dynamic_lds_size
    .group_segment_fixed_size: 16384
    .kernarg_segment_align: 8
    .kernarg_segment_size: 528
    .language:       OpenCL C
    .language_version:
      - 2
      - 0
    .max_flat_workgroup_size: 512
    .name:           _Z10hybrid_fwd6Params
    .private_segment_fixed_size: 0
    .sgpr_count:     104
    .sgpr_spill_count: 60
    .symbol:         _Z10hybrid_fwd6Params.kd
    .uniform_work_group_size: 1
    .uses_dynamic_stack: false
    .vgpr_count:     256
    .vgpr_spill_count: 0
    .wavefront_size: 64
